# P8 residual tile touched at phase start; UX copy both halves per wait; K relayout touches next batch strides early
# baseline (speedup 1.0000x reference)
.LBB0_412:
	v_ashrrev_i32_e32 v7, 31, v5
	v_mov_b32_e32 v6, v5
	v_lshrrev_b32_e32 v9, 3, v0
	v_lshlrev_b64 v[10:11], 12, v[6:7]
	s_movk_i32 s3, 0xfff
	v_and_or_b32 v9, v9, s3, v10
	v_mov_b64_e32 v[12:13], s[12:13]
	v_bfe_u32 v16, v0, 15, 2
	v_mad_u64_u32 v[12:13], s[4:5], v9, s76, v[12:13]
	v_mad_i32_i24 v13, v11, s76, v13
	v_lshlrev_b32_e32 v64, 7, v16
	v_lshl_add_u64 v[10:11], v[12:13], 0, v[64:65]
	v_lshlrev_b32_e32 v64, 1, v2
	v_lshl_add_u64 v[10:11], v[10:11], 0, v[64:65]
	v_add_co_u32_e32 v10, vcc, s77, v10
	s_mov_b32 s4, 0x3e38aa3b
	s_nop 0
	v_addc_co_u32_e32 v11, vcc, 0, v11, vcc
	s_mov_b32 s98, 0x1e00000
	s_mov_b32 s99, 0
	v_lshl_add_u64 v[80:81], v[10:11], 0, s[98:99]
	global_load_dwordx4 v[84:87], v[80:81], off offset:1024
	v_lshl_add_u64 v[80:81], v[80:81], 0, s[98:99]
	global_load_dwordx4 v[88:91], v[80:81], off offset:1024
	v_lshl_add_u64 v[80:81], v[80:81], 0, s[98:99]
	global_load_dwordx4 v[92:95], v[80:81], off offset:1024
	global_load_dwordx4 v[10:13], v[10:11], off offset:1024
	v_lshlrev_b64 v[6:7], 21, v[6:7]
	v_lshl_add_u64 v[6:7], s[88:89], 0, v[6:7]
	v_lshlrev_b32_e32 v9, 4, v0
	s_or_b64 s[42:43], s[42:43], exec
	s_waitcnt vmcnt(0)
	v_lshlrev_b32_e32 v14, 16, v10
	v_and_b32_e32 v15, 0xffff0000, v10
	v_pk_mul_f32 v[14:15], v[14:15], s[4:5] op_sel_hi:[1,0]
	s_nop 0
	v_cvt_pk_bf16_f32 v10, v14, v15
	v_lshlrev_b32_e32 v14, 16, v11
	v_and_b32_e32 v15, 0xffff0000, v11
	v_pk_mul_f32 v[14:15], v[14:15], s[4:5] op_sel_hi:[1,0]
	s_nop 0
	v_cvt_pk_bf16_f32 v11, v14, v15
	v_lshlrev_b32_e32 v14, 16, v12
	v_and_b32_e32 v15, 0xffff0000, v12
	v_pk_mul_f32 v[14:15], v[14:15], s[4:5] op_sel_hi:[1,0]
	s_nop 0
	v_cvt_pk_bf16_f32 v12, v14, v15
	v_lshlrev_b32_e32 v14, 16, v13
	v_and_b32_e32 v15, 0xffff0000, v13
	v_pk_mul_f32 v[14:15], v[14:15], s[4:5] op_sel_hi:[1,0]
	s_mov_b64 s[4:5], 0x80000
	v_cvt_pk_bf16_f32 v13, v14, v15
	v_lshlrev_b32_e32 v14, 19, v16
	v_mov_b32_e32 v15, v65
	v_lshl_add_u64 v[6:7], v[6:7], 0, v[14:15]
	v_and_b32_e32 v14, 0x7e000, v9
	v_and_b32_e32 v9, 0x100, v0
	v_lshl_add_u64 v[6:7], v[6:7], 0, v[14:15]
	v_bfe_u32 v14, v0, 3, 5
	v_and_or_b32 v9, v8, 32, v9
	v_or3_b32 v9, v9, v14, v3
	v_lshlrev_b32_e32 v14, 4, v9
	v_lshl_add_u64 v[6:7], v[6:7], 0, v[14:15]
	global_store_dwordx4 v[6:7], v[10:13], off
	v_lshl_add_u64 v[6:7], v[0:1], 0, s[96:97]
	v_cmp_gt_i64_e32 vcc, s[4:5], v[6:7]
	s_and_saveexec_b64 s[46:47], vcc
	s_cbranch_execz .LBB0_411
	v_readlane_b32 s4, v253, 36
	v_readlane_b32 s5, v253, 37
	v_readlane_b32 s3, v253, 58
	s_nop 0
	v_lshl_add_u64 v[10:11], s[4:5], 0, v[4:5]
	v_add_u32_e32 v9, s3, v0
	v_ashrrev_i32_e32 v15, 31, v11
	v_mov_b32_e32 v14, v11
	v_lshrrev_b32_e32 v12, 3, v9
	v_lshlrev_b64 v[10:11], 12, v[14:15]
	s_movk_i32 s3, 0xfff
	v_and_or_b32 v10, v12, s3, v10
	v_mov_b64_e32 v[12:13], s[12:13]
	v_bfe_u32 v18, v9, 15, 2
	v_mad_u64_u32 v[12:13], s[4:5], v10, s76, v[12:13]
	v_mad_i32_i24 v13, v11, s76, v13
	v_lshlrev_b32_e32 v10, 7, v18
	v_mov_b32_e32 v11, v65
	v_lshl_add_u64 v[10:11], v[12:13], 0, v[10:11]
	v_lshl_add_u64 v[10:11], v[10:11], 0, v[64:65]
	v_add_co_u32_e32 v10, vcc, s77, v10
	s_mov_b32 s4, 0x3e38aa3b
	s_nop 0
	v_addc_co_u32_e32 v11, vcc, 0, v11, vcc
	global_load_dwordx4 v[10:13], v[10:11], off offset:1024
	v_lshlrev_b64 v[14:15], 21, v[14:15]
	v_lshl_add_u64 v[14:15], s[88:89], 0, v[14:15]
	v_readlane_b32 s3, v253, 59
	s_waitcnt vmcnt(0)
	v_lshlrev_b32_e32 v16, 16, v10
	v_and_b32_e32 v17, 0xffff0000, v10
	v_pk_mul_f32 v[16:17], v[16:17], s[4:5] op_sel_hi:[1,0]
	s_nop 0
	v_cvt_pk_bf16_f32 v10, v16, v17
	v_lshlrev_b32_e32 v16, 16, v11
	v_and_b32_e32 v17, 0xffff0000, v11
	v_pk_mul_f32 v[16:17], v[16:17], s[4:5] op_sel_hi:[1,0]
	s_nop 0
	v_cvt_pk_bf16_f32 v11, v16, v17
	v_lshlrev_b32_e32 v16, 16, v12
	v_and_b32_e32 v17, 0xffff0000, v12
	v_pk_mul_f32 v[16:17], v[16:17], s[4:5] op_sel_hi:[1,0]
	s_nop 0
	v_cvt_pk_bf16_f32 v12, v16, v17
	v_lshlrev_b32_e32 v16, 16, v13
	v_and_b32_e32 v17, 0xffff0000, v13
	v_pk_mul_f32 v[16:17], v[16:17], s[4:5] op_sel_hi:[1,0]
	v_readlane_b32 s4, v253, 44
	v_cvt_pk_bf16_f32 v13, v16, v17
	v_lshlrev_b32_e32 v16, 19, v18
	v_mov_b32_e32 v17, v65
	v_lshl_add_u64 v[14:15], v[14:15], 0, v[16:17]
	v_lshlrev_b32_e32 v16, 4, v9
	v_and_b32_e32 v16, 0x7e000, v16
	v_lshl_add_u64 v[14:15], v[14:15], 0, v[16:17]
	v_and_b32_e32 v16, 0x100, v9
	v_add_u32_e32 v17, s3, v8
	v_bfe_u32 v9, v9, 3, 5
	v_and_or_b32 v16, v17, 32, v16
	v_or3_b32 v9, v16, v9, v3
	v_lshlrev_b32_e32 v16, 4, v9
	v_mov_b32_e32 v17, v65
	v_lshl_add_u64 v[14:15], v[14:15], 0, v[16:17]
	v_readlane_b32 s5, v253, 45
	global_store_dwordx4 v[14:15], v[10:13], off
	s_nop 1
	v_lshl_add_u64 v[10:11], s[4:5], 0, v[0:1]
	s_mov_b64 s[4:5], 0x80000
	v_cmp_gt_i64_e32 vcc, s[4:5], v[10:11]
	s_mov_b64 s[4:5], -1
	s_and_saveexec_b64 s[38:39], vcc
	s_cbranch_execz .LBB0_410
	v_readlane_b32 s4, v253, 42
	v_readlane_b32 s5, v253, 43
	v_readlane_b32 s3, v253, 63
	s_mov_b64 s[6:7], -1
	v_lshl_add_u64 v[10:11], s[4:5], 0, v[4:5]
	v_add_u32_e32 v9, s3, v0
	v_ashrrev_i32_e32 v15, 31, v11
	v_mov_b32_e32 v14, v11
	v_lshrrev_b32_e32 v12, 3, v9
	v_lshlrev_b64 v[10:11], 12, v[14:15]
	s_movk_i32 s3, 0xfff
	v_and_or_b32 v10, v12, s3, v10
	v_mov_b64_e32 v[12:13], s[12:13]
	v_bfe_u32 v18, v9, 15, 2
	v_mad_u64_u32 v[12:13], s[4:5], v10, s76, v[12:13]
	v_mad_i32_i24 v13, v11, s76, v13
	v_lshlrev_b32_e32 v10, 7, v18
	v_mov_b32_e32 v11, v65
	v_lshl_add_u64 v[10:11], v[12:13], 0, v[10:11]
	v_lshl_add_u64 v[10:11], v[10:11], 0, v[64:65]
	v_add_co_u32_e32 v10, vcc, s77, v10
	s_mov_b32 s4, 0x3e38aa3b
	s_nop 0
	v_addc_co_u32_e32 v11, vcc, 0, v11, vcc
	global_load_dwordx4 v[10:13], v[10:11], off offset:1024
	v_lshlrev_b64 v[14:15], 21, v[14:15]
	v_lshl_add_u64 v[14:15], s[88:89], 0, v[14:15]
	v_readlane_b32 s3, v253, 62
	s_waitcnt vmcnt(0)
	v_lshlrev_b32_e32 v16, 16, v10
	v_and_b32_e32 v17, 0xffff0000, v10
	v_pk_mul_f32 v[16:17], v[16:17], s[4:5] op_sel_hi:[1,0]
	s_nop 0
	v_cvt_pk_bf16_f32 v10, v16, v17
	v_lshlrev_b32_e32 v16, 16, v11
	v_and_b32_e32 v17, 0xffff0000, v11
	v_pk_mul_f32 v[16:17], v[16:17], s[4:5] op_sel_hi:[1,0]
	s_nop 0
	v_cvt_pk_bf16_f32 v11, v16, v17
	v_lshlrev_b32_e32 v16, 16, v12
	v_and_b32_e32 v17, 0xffff0000, v12
	v_pk_mul_f32 v[16:17], v[16:17], s[4:5] op_sel_hi:[1,0]
	s_nop 0
	v_cvt_pk_bf16_f32 v12, v16, v17
	v_lshlrev_b32_e32 v16, 16, v13
	v_and_b32_e32 v17, 0xffff0000, v13
	v_pk_mul_f32 v[16:17], v[16:17], s[4:5] op_sel_hi:[1,0]
	v_readlane_b32 s4, v253, 32
	v_cvt_pk_bf16_f32 v13, v16, v17
	v_lshlrev_b32_e32 v16, 19, v18
	v_mov_b32_e32 v17, v65
	v_lshl_add_u64 v[14:15], v[14:15], 0, v[16:17]
	v_lshlrev_b32_e32 v16, 4, v9
	v_and_b32_e32 v16, 0x7e000, v16
	v_lshl_add_u64 v[14:15], v[14:15], 0, v[16:17]
	v_and_b32_e32 v16, 0x100, v9
	v_add_u32_e32 v17, s3, v8
	v_bfe_u32 v9, v9, 3, 5
	v_and_or_b32 v16, v17, 32, v16
	v_or3_b32 v9, v16, v9, v3
	v_lshlrev_b32_e32 v16, 4, v9
	v_mov_b32_e32 v17, v65
	v_lshl_add_u64 v[14:15], v[14:15], 0, v[16:17]
	v_readlane_b32 s5, v253, 33
	global_store_dwordx4 v[14:15], v[10:13], off
	s_nop 1
	v_lshl_add_u64 v[10:11], s[4:5], 0, v[0:1]
	s_mov_b64 s[4:5], 0x80000
	v_cmp_gt_i64_e32 vcc, s[4:5], v[10:11]
	s_and_saveexec_b64 s[4:5], vcc
	s_cbranch_execz .LBB0_409
	v_readlane_b32 s6, v253, 30
	s_mul_i32 s3, s86, 0x600
	v_readlane_b32 s7, v253, 31
	v_add_u32_e32 v9, s3, v0
	v_lshrrev_b32_e32 v10, 3, v9
	v_lshl_add_u64 v[0:1], s[6:7], 0, v[4:5]
	v_ashrrev_i32_e32 v15, 31, v1
	v_mov_b32_e32 v14, v1
	v_lshlrev_b64 v[0:1], 12, v[14:15]
	s_movk_i32 s3, 0xfff
	v_and_or_b32 v0, v10, s3, v0
	v_mov_b64_e32 v[10:11], s[12:13]
	v_bfe_u32 v16, v9, 15, 2
	v_mad_u64_u32 v[10:11], s[6:7], v0, s76, v[10:11]
	v_mad_i32_i24 v11, v1, s76, v11
	v_lshlrev_b32_e32 v0, 7, v16
	v_mov_b32_e32 v1, v65
	v_lshl_add_u64 v[0:1], v[10:11], 0, v[0:1]
	v_lshl_add_u64 v[0:1], v[0:1], 0, v[64:65]
	v_add_co_u32_e32 v0, vcc, s77, v0
	s_mov_b32 s6, 0x3e38aa3b
	s_nop 0
	v_addc_co_u32_e32 v1, vcc, 0, v1, vcc
	global_load_dwordx4 v[10:13], v[0:1], off offset:1024
	v_lshlrev_b32_e32 v64, 19, v16
	s_mul_i32 s3, s86, 0xc000
	s_waitcnt vmcnt(0)
	v_lshlrev_b32_e32 v0, 16, v10
	v_and_b32_e32 v1, 0xffff0000, v10
	v_pk_mul_f32 v[0:1], v[0:1], s[6:7] op_sel_hi:[1,0]
	s_nop 0
	v_cvt_pk_bf16_f32 v10, v0, v1
	v_lshlrev_b32_e32 v0, 16, v11
	v_and_b32_e32 v1, 0xffff0000, v11
	v_pk_mul_f32 v[0:1], v[0:1], s[6:7] op_sel_hi:[1,0]
	s_nop 0
	v_cvt_pk_bf16_f32 v11, v0, v1
	v_lshlrev_b32_e32 v0, 16, v12
	v_and_b32_e32 v1, 0xffff0000, v12
	v_pk_mul_f32 v[0:1], v[0:1], s[6:7] op_sel_hi:[1,0]
	s_nop 0
	v_cvt_pk_bf16_f32 v12, v0, v1
	v_lshlrev_b32_e32 v0, 16, v13
	v_and_b32_e32 v1, 0xffff0000, v13
	v_pk_mul_f32 v[0:1], v[0:1], s[6:7] op_sel_hi:[1,0]
	s_nop 0
	v_cvt_pk_bf16_f32 v13, v0, v1
	v_lshlrev_b64 v[0:1], 21, v[14:15]
	v_lshl_add_u64 v[0:1], s[88:89], 0, v[0:1]
	v_lshlrev_b32_e32 v14, 4, v9
	v_lshl_add_u64 v[0:1], v[0:1], 0, v[64:65]
	v_and_b32_e32 v64, 0x7e000, v14
	v_and_b32_e32 v14, 0x100, v9
	v_add_u32_e32 v15, s3, v8
	v_bfe_u32 v9, v9, 3, 5
	v_and_or_b32 v14, v15, 32, v14
	s_add_u32 s3, s96, s96
	v_or3_b32 v9, v14, v9, v3
	s_addc_u32 s7, s97, s97
	v_lshl_add_u64 v[0:1], v[0:1], 0, v[64:65]
	v_lshlrev_b32_e32 v64, 4, v9
	s_add_u32 s6, s3, s96
	v_lshl_add_u64 v[0:1], v[0:1], 0, v[64:65]
	s_addc_u32 s7, s7, s97
	global_store_dwordx4 v[0:1], v[10:13], off
	v_lshl_add_u64 v[0:1], s[6:7], 0, v[6:7]
	v_readlane_b32 s6, v253, 40
	v_readlane_b32 s7, v253, 41
	v_readlane_b32 s3, v253, 61
	s_nop 0
	v_lshl_add_u64 v[4:5], v[4:5], 0, s[6:7]
	s_mov_b64 s[6:7], 0x7ffff
	v_cmp_lt_i64_e32 vcc, s[6:7], v[0:1]
	v_add_u32_e32 v8, s3, v8
	s_orn2_b64 s[6:7], vcc, exec
	s_branch .LBB0_409

.LBB0_426:
	v_alignbit_b32 v7, v17, v16, 4
	v_mov_b64_e32 v[4:5], s[12:13]
	v_and_b32_e32 v6, 0xf0, v2
	v_mad_i64_i32 v[4:5], s[6:7], v7, s76, v[4:5]
	v_lshlrev_b32_e32 v64, 1, v6
	v_lshl_add_u64 v[4:5], v[4:5], 0, v[64:65]
	s_mov_b64 s[6:7], 0x1a00
	v_ashrrev_i32_e32 v7, 6, v7
	v_lshl_add_u64 v[12:13], v[4:5], 0, s[6:7]
	v_and_b32_e32 v6, 0xf00, v0
	v_and_b32_e32 v7, 0xffffffc0, v7
	v_readlane_b32 s6, v252, 47
	v_lshrrev_b32_e32 v8, 10, v16
	v_add_u32_e32 v7, v6, v7
	v_readlane_b32 s7, v252, 48
	v_and_or_b32 v7, v8, 63, v7
	v_add_co_u32_e32 v4, vcc, 0x1000, v4
	v_mov_b64_e32 v[8:9], s[6:7]
	v_mad_i64_i32 v[8:9], s[6:7], v7, s33, v[8:9]
	v_and_b32_e32 v7, 0x3f0, v16
	v_lshlrev_b32_e32 v10, 1, v7
	v_mov_b32_e32 v11, v65
	v_addc_co_u32_e32 v5, vcc, 0, v5, vcc
	v_lshl_add_u64 v[14:15], v[8:9], 0, v[10:11]
	global_load_dwordx4 v[84:87], v[12:13], off offset:16
	global_load_dwordx4 v[8:11], v[4:5], off offset:2560
	v_lshl_add_u64 v[4:5], v[16:17], 0, s[96:97]
	s_mov_b64 s[6:7], 0x40000
	v_cmp_gt_i64_e32 vcc, s[6:7], v[4:5]
	s_or_b64 s[38:39], s[38:39], exec
	s_waitcnt vmcnt(0)
	global_store_dwordx4 v[14:15], v[8:11], off
	s_nop 0
	s_nop 0
	global_store_dwordx4 v[14:15], v[84:87], off offset:16
	s_and_saveexec_b64 s[6:7], vcc
	s_cbranch_execz .LBB0_425
	v_alignbit_b32 v7, v5, v4, 4
	v_mov_b64_e32 v[8:9], s[12:13]
	v_mad_i64_i32 v[8:9], s[8:9], v7, s76, v[8:9]
	v_lshl_add_u64 v[8:9], v[8:9], 0, v[64:65]
	s_mov_b64 s[8:9], 0x1a00
	v_ashrrev_i32_e32 v7, 6, v7
	v_lshl_add_u64 v[10:11], v[8:9], 0, s[8:9]
	v_and_b32_e32 v7, 0xffffffc0, v7
	v_readlane_b32 s8, v252, 47
	v_lshrrev_b32_e32 v12, 10, v4
	v_add_u32_e32 v6, v6, v7
	v_readlane_b32 s9, v252, 48
	v_and_or_b32 v12, v12, 63, v6
	v_lshl_add_u64 v[16:17], v[4:5], 0, s[96:97]
	v_mov_b64_e32 v[6:7], s[8:9]
	v_mad_i64_i32 v[6:7], s[8:9], v12, s33, v[6:7]
	v_and_b32_e32 v12, 0x3f0, v4
	v_lshlrev_b32_e32 v64, 1, v12
	v_lshl_add_u64 v[12:13], v[6:7], 0, v[64:65]
	v_add_co_u32_e32 v6, vcc, 0x1000, v8
	v_readlane_b32 s8, v253, 48
	s_nop 0
	v_addc_co_u32_e32 v7, vcc, 0, v9, vcc
	global_load_dwordx4 v[88:91], v[10:11], off offset:16
	global_load_dwordx4 v[6:9], v[6:7], off offset:2560
	v_readlane_b32 s9, v253, 49
	s_waitcnt vmcnt(0)
	global_store_dwordx4 v[12:13], v[6:9], off
	s_nop 0
	v_lshl_add_u64 v[0:1], v[0:1], 0, s[8:9]
	v_readlane_b32 s8, v253, 50
	v_readlane_b32 s9, v253, 51
	s_nop 0
	global_store_dwordx4 v[12:13], v[88:91], off offset:16
	v_lshl_add_u64 v[2:3], v[2:3], 0, s[8:9]
	s_mov_b64 s[8:9], 0x3ffff
	v_cmp_lt_i64_e32 vcc, s[8:9], v[16:17]
	s_andn2_b64 s[8:9], s[38:39], exec
	s_and_b64 s[18:19], vcc, exec
	s_or_b64 s[38:39], s[8:9], s[18:19]
	s_branch .LBB0_425

.LBB0_948:
	s_or_b64 exec, exec, s[0:1]
	v_readlane_b32 s0, v255, 15
	v_mov_b32_e32 v6, v210
	v_readlane_b32 s1, v255, 16
	s_waitcnt lgkmcnt(0)
	s_barrier
	s_and_b64 vcc, exec, s[0:1]
	v_readfirstlane_b32 s4, v6
	s_cbranch_vccnz .LBB0_964
	v_readlane_b32 s98, v255, 9
	v_readlane_b32 s99, v255, 10
	v_readlane_b32 s100, v253, 19
	v_readlane_b32 s101, v253, 23
	s_lshl_b32 s100, s100, 20
	s_lshl_b32 s101, s101, 10
	s_add_i32 s100, s100, s101
	s_add_u32 s98, s98, s100
	s_addc_u32 s99, s99, 0
	v_lshrrev_b32_e32 v0, 6, v210
	v_and_b32_e32 v1, 63, v210
	v_lshl_or_b32 v0, v0, 8, v1
	v_lshrrev_b32_e32 v1, 3, v0
	v_and_b32_e32 v0, 7, v0
	v_lshlrev_b32_e32 v1, 12, v1
	v_lshl_or_b32 v0, v0, 7, v1
	v_mov_b32_e32 v1, 0
	v_lshl_add_u64 v[0:1], s[98:99], 0, v[0:1]
	s_mov_b32 s100, 0x8000
	s_mov_b32 s101, 0
	s_mov_b32 m0, 0x21000
	s_nop 0
	global_load_lds_dword v[0:1], off
	v_lshl_add_u64 v[0:1], v[0:1], 0, s[100:101]
	global_load_lds_dword v[0:1], off
	v_lshl_add_u64 v[0:1], v[0:1], 0, s[100:101]
	global_load_lds_dword v[0:1], off
	v_lshl_add_u64 v[0:1], v[0:1], 0, s[100:101]
	global_load_lds_dword v[0:1], off
	v_lshlrev_b32_e32 v3, 4, v6
	v_add_u32_e32 v1, 0x2000, v3
	v_ashrrev_i32_e32 v0, 31, v1
	v_lshrrev_b32_e32 v0, 22, v0
	v_add_u32_e32 v0, v1, v0
	v_ashrrev_i32_e32 v0, 10, v0
	v_mul_i32_i24_e32 v2, 0x400, v0
	v_sub_u32_e32 v1, v1, v2
	v_lshrrev_b32_e32 v2, 4, v1
	v_bitop3_b32 v2, v2, v1, 32 bitop3:0x6c
	v_ashrrev_i32_e32 v1, 31, v2
	v_lshrrev_b32_e32 v1, 26, v1
	v_add_u32_e32 v4, v2, v1
	v_lshlrev_b32_e32 v5, 3, v0
	v_ashrrev_i32_e32 v1, 6, v4
	v_and_b32_e32 v5, -16, v5
	v_add_u32_e32 v5, v1, v5
	v_and_b32_e32 v7, 3, v1
	s_mov_b32 s0, 0x1fffe0
	v_lshrrev_b32_e32 v8, 2, v5
	v_lshlrev_b32_e32 v9, 1, v5
	v_and_b32_e32 v4, 0xc0, v4
	v_and_or_b32 v7, v5, s0, v7
	v_and_b32_e32 v8, 4, v8
	v_and_b32_e32 v9, 24, v9
	v_sub_u32_e32 v2, v2, v4
	v_mov_b32_e32 v12, 1
	v_or3_b32 v7, v7, v8, v9
	v_lshlrev_b32_e32 v8, 5, v0
	v_ashrrev_i16_sdwa v2, v12, sext(v2) dst_sel:DWORD dst_unused:UNUSED_PAD src0_sel:DWORD src1_sel:BYTE_0
	v_and_b32_e32 v8, 32, v8
	v_bfe_i32 v2, v2, 0, 16
	v_add_lshl_u32 v4, v8, v2, 1
	v_lshl_add_u32 v130, v7, 11, v4
	v_lshl_add_u32 v132, v5, 11, v4
	v_bfe_i32 v4, v6, 27, 1
	v_lshrrev_b32_e32 v4, 22, v4
	v_add_u32_e32 v4, v3, v4
	v_and_b32_e32 v4, 0xfffffc00, v4
	v_sub_u32_e32 v3, v3, v4
	v_lshrrev_b32_e32 v4, 4, v3
	v_bitop3_b32 v5, v4, v3, 32 bitop3:0x6c
	v_ashrrev_i32_e32 v4, 31, v6
	v_lshrrev_b32_e32 v4, 26, v4
	v_ashrrev_i32_e32 v3, 31, v5
	v_add_u32_e32 v4, v6, v4
	v_lshrrev_b32_e32 v3, 26, v3
	v_ashrrev_i32_e32 v4, 6, v4
	v_add_u32_e32 v7, v5, v3
	v_lshlrev_b32_e32 v8, 3, v4
	v_ashrrev_i32_e32 v3, 6, v7
	v_and_b32_e32 v8, -16, v8
	v_add_u32_e32 v8, v3, v8
	v_and_b32_e32 v9, 3, v3
	v_lshrrev_b32_e32 v10, 2, v8
	v_lshlrev_b32_e32 v11, 1, v8
	v_and_b32_e32 v7, 0xc0, v7
	v_and_or_b32 v9, v8, s0, v9
	v_and_b32_e32 v10, 4, v10
	v_and_b32_e32 v11, 24, v11
	v_sub_u32_e32 v5, v5, v7
	s_ashr_i32 s3, s4, 6
	v_or3_b32 v9, v9, v10, v11
	v_lshlrev_b32_e32 v10, 5, v4
	v_ashrrev_i16_sdwa v5, v12, sext(v5) dst_sel:DWORD dst_unused:UNUSED_PAD src0_sel:DWORD src1_sel:BYTE_0
	s_lshl_b32 s8, s3, 10
	v_and_b32_e32 v10, 32, v10
	v_bfe_i32 v5, v5, 0, 16
	v_add_lshl_u32 v7, v10, v5, 1
	s_add_i32 s9, s8, 0
	v_readlane_b32 s0, v254, 56
	v_lshl_add_u32 v64, v9, 11, v7
	s_add_i32 m0, s9, 0x10000
	v_readlane_b32 s1, v254, 57
	v_lshl_add_u32 v134, v8, 11, v7
	s_add_i32 s18, s9, 0x2000
	s_add_i32 s19, s9, 0x4000
	s_add_i32 s20, s9, 0x6000
	s_ashr_i32 s5, s4, 8
	global_load_lds_dwordx4 v64, s[0:1]
	s_add_i32 m0, s9, 0x12000
	s_nop 0
	global_load_lds_dwordx4 v130, s[0:1]
	v_readlane_b32 s0, v254, 54
	s_add_i32 m0, s9, 0x14000
	v_readlane_b32 s1, v254, 55
	s_nop 4
	global_load_lds_dwordx4 v64, s[0:1]
	s_add_i32 m0, s9, 0x16000
	s_cmp_eq_u32 s5, 1
	global_load_lds_dwordx4 v130, s[0:1]
	v_readlane_b32 s0, v253, 26
	s_mov_b32 m0, s9
	v_readlane_b32 s1, v253, 27
	s_nop 4
	global_load_lds_dwordx4 v134, s[0:1]
	s_mov_b32 m0, s18
	s_nop 0
	global_load_lds_dwordx4 v132, s[0:1]
	v_readlane_b32 s0, v253, 28
	s_mov_b32 m0, s19
	v_readlane_b32 s1, v253, 29
	s_nop 4
	global_load_lds_dwordx4 v134, s[0:1]
	s_mov_b32 m0, s20
	s_nop 0
	global_load_lds_dwordx4 v132, s[0:1]
	s_cselect_b64 s[0:1], -1, 0
	s_cmp_lg_u32 s5, 1
	s_cbranch_scc1 .LBB0_951
	s_barrier

	.amdhsa_kernel _Z4mega4Args
		.amdhsa_group_segment_fixed_size 0
		.amdhsa_private_segment_fixed_size 0
		.amdhsa_kernarg_size 440
		.amdhsa_user_sgpr_count 2
		.amdhsa_user_sgpr_dispatch_ptr 0
		.amdhsa_user_sgpr_queue_ptr 0
		.amdhsa_user_sgpr_kernarg_segment_ptr 1
		.amdhsa_user_sgpr_dispatch_id 0
		.amdhsa_user_sgpr_kernarg_preload_length 0
		.amdhsa_user_sgpr_kernarg_preload_offset 0
		.amdhsa_user_sgpr_private_segment_size 0
		.amdhsa_uses_dynamic_stack 0
		.amdhsa_enable_private_segment 0
		.amdhsa_system_sgpr_workgroup_id_x 1
		.amdhsa_system_sgpr_workgroup_id_y 0
		.amdhsa_system_sgpr_workgroup_id_z 0
		.amdhsa_system_sgpr_workgroup_info 0
		.amdhsa_system_vgpr_workitem_id 2
		.amdhsa_next_free_vgpr 256
		.amdhsa_next_free_sgpr 102
		.amdhsa_accum_offset 256
		.amdhsa_reserve_vcc 1
		.amdhsa_float_round_mode_32 0
		.amdhsa_float_round_mode_16_64 0
		.amdhsa_float_denorm_mode_32 3
		.amdhsa_float_denorm_mode_16_64 3
		.amdhsa_dx10_clamp 1
		.amdhsa_ieee_mode 1
		.amdhsa_fp16_overflow 0
		.amdhsa_tg_split 0
		.amdhsa_exception_fp_ieee_invalid_op 0
		.amdhsa_exception_fp_denorm_src 0
		.amdhsa_exception_fp_ieee_div_zero 0
		.amdhsa_exception_fp_ieee_overflow 0
		.amdhsa_exception_fp_ieee_underflow 0
		.amdhsa_exception_fp_ieee_inexact 0
		.amdhsa_exception_int_div_zero 0
	.end_amdhsa_kernel

amdhsa.kernels:
  - .agpr_count:     0
    .args:
      - .offset:         0
        .size:           184
        .value_kind:     by_value
      - .offset:         184
        .size:           4
        .value_kind:     hidden_block_count_x
      - .offset:         188
        .size:           4
        .value_kind:     hidden_block_count_y
      - .offset:         192
        .size:           4
        .value_kind:     hidden_block_count_z
      - .offset:         196
        .size:           2
        .value_kind:     hidden_group_size_x
      - .offset:         198
        .size:           2
        .value_kind:     hidden_group_size_y
      - .offset:         200
        .size:           2
        .value_kind:     hidden_group_size_z
      - .offset:         202
        .size:           2
        .value_kind:     hidden_remainder_x
      - .offset:         204
        .size:           2
        .value_kind:     hidden_remainder_y
      - .offset:         206
        .size:           2
        .value_kind:     hidden_remainder_z
      - .offset:         224
        .size:           8
        .value_kind:     hidden_global_offset_x
      - .offset:         232
        .size:           8
        .value_kind:     hidden_global_offset_y
      - .offset:         240
        .size:           8
        .value_kind:     hidden_global_offset_z
      - .offset:         248
        .size:           2
        .value_kind:     hidden_grid_dims
      - .offset:         272
        .size:           8
        .value_kind:     hidden_multigrid_sync_arg
      - .offset:         304
        .size:           4
        .value_kind:     hidden_dynamic_lds_size
    .group_segment_fixed_size: 0
    .kernarg_segment_align: 8
    .kernarg_segment_size: 440
    .language:       OpenCL C
    .language_version:
      - 2
      - 0
    .max_flat_workgroup_size: 512
    .name:           _Z4mega4Args
    .private_segment_fixed_size: 0
    .sgpr_count:     108
    .sgpr_spill_count: 337
    .symbol:         _Z4mega4Args.kd
    .uniform_work_group_size: 1
    .uses_dynamic_stack: false
    .vgpr_count:     256
    .vgpr_spill_count: 0
    .wavefront_size: 64
